# gate-prep: top-of-item wait relaxed to vmcnt(9): the four chunk-decay stores are always issued, so nine younger stores may stay in flight
# speedup vs baseline: 1.0086x; 1.0086x over previous
; #define LAS __attribute__((address_space(3)))
; __device__ __forceinline__ size_t PIX(int row, int col) { return (size_t)(col >> 7) * PSLOT + (size_t)row * 128 + (col & 127); }
; __device__ __forceinline__ int opaque_tid() { int t = threadIdx.x; asm volatile("" : "+v"(t)); return t; }
; __device__ void prep_item(const Params& p, int l, int item, LAS unsigned char* lds) {
;     const int tid = opaque_tid(), w = tid >> 6, lane = tid & 63;
;     const int tau = lane & 31, kh = lane >> 5, k0 = 16 * w + 8 * kh, l15 = lane & 15, q4 = lane >> 4;
;     const int ci = item % NCH, bh = item / NCH, h = bh & 3, b = bh >> 2;
;     const int R0 = ci < 8 ? NLAT + b * 256 + 32 * ci : b * 4096 + 32 * (ci - 8);
;     bf16_t* P = (bf16_t*)(p.ws + WS_BIG);
;     const bool first = (l == 0);
;     const bool want_out = first || ci >= 8;
;     for (int dd = 0; dd < 2; ++dd) { LAS unsigned* az = (LAS unsigned*)(lds + dd * P1_DIRSZ + P1_AW) + w * (32 * KT_ST / 2); for (int i = lane; i < 32 * KT_ST / 2; i += 64) az[i] = 0u; }
;     u32x4 rf0, rq0, rv0, rf1, rq1, rv1;
;     { const int r_ = R0 + tau; rf0 = *(const u32x4*)(P + PIX(r_, h * 128 + k0)); rq0 = *(const u32x4*)(P + PIX(r_, 1536 + h * 128 + k0)); rv0 = *(const u32x4*)(P + PIX(r_, 1024 + h * 128 + k0)); }
;     { const int r_ = R0 + 31 - tau; rf1 = *(const u32x4*)(P + PIX(r_, 512 + h * 128 + k0)); rq1 = *(const u32x4*)(P + PIX(r_, 1536 + h * 128 + k0)); rv1 = *(const u32x4*)(P + PIX(r_, 1024 + h * 128 + k0)); }
;     asm volatile("s_waitcnt vmcnt(0)" ::: "memory");
;     __syncthreads();
.LBB0_247:
	v_ashrrev_i32_e32 v1, 6, v54
	s_and_b32 s74, s6, 3
	v_lshlrev_b32_e32 v30, 4, v1
	s_lshl_b32 s6, s74, 7
	v_and_b32_e32 v31, 31, v54
	v_lshrrev_b32_e32 v0, 2, v54
	v_add_u32_e32 v3, s6, v30
	v_and_b32_e32 v0, 8, v0
	v_add_u32_e32 v2, s70, v31
	v_ashrrev_i32_e32 v4, 7, v3
	v_mov_b32_e32 v3, v8
	s_movk_i32 s0, 0x78
	v_mov_b64_e32 v[10:11], s[82:83]
	v_bitop3_b32 v6, v30, s0, v0 bitop3:0xc8
	v_mad_i64_i32 v[4:5], s[0:1], v4, s87, v[10:11]
	v_lshlrev_b64 v[36:37], 8, v[2:3]
	s_or_b32 s7, s6, 0x600
	v_lshl_add_u64 v[2:3], v[4:5], 0, v[36:37]
	v_add_u32_e32 v4, s7, v30
	v_ashrrev_i32_e32 v4, 7, v4
	v_lshlrev_b32_e32 v12, 1, v6
	v_mov_b32_e32 v13, v8
	v_mad_i64_i32 v[14:15], s[0:1], v4, s87, v[10:11]
	v_lshl_add_u64 v[2:3], v[2:3], 0, v[12:13]
	v_lshl_add_u64 v[4:5], v[14:15], 0, v[36:37]
	v_lshl_add_u64 v[16:17], v[4:5], 0, v[12:13]
	s_or_b32 s72, s6, 0x400
	s_or_b32 s71, s6, 0x200
	v_add_u32_e32 v2, s72, v30
	v_bitop3_b32 v56, v54, 31, v54 bitop3:0xc
	v_add_u32_e32 v9, s71, v30
	v_ashrrev_i32_e32 v2, 7, v2
	v_add_u32_e32 v18, s70, v56
	v_ashrrev_i32_e32 v9, 7, v9
	v_mov_b32_e32 v19, v8
	v_mad_i64_i32 v[2:3], s[0:1], v2, s87, v[10:11]
	v_mad_i64_i32 v[10:11], s[0:1], v9, s87, v[10:11]
	v_lshlrev_b64 v[32:33], 8, v[18:19]
	v_lshl_add_u64 v[16:17], v[2:3], 0, v[36:37]
	v_lshl_add_u64 v[10:11], v[10:11], 0, v[32:33]
	v_lshl_add_u64 v[16:17], v[16:17], 0, v[12:13]
	v_lshl_add_u64 v[10:11], v[10:11], 0, v[12:13]
	v_lshl_add_u64 v[10:11], v[14:15], 0, v[32:33]
	v_lshl_add_u64 v[10:11], v[10:11], 0, v[12:13]
	v_lshl_add_u64 v[2:3], v[2:3], 0, v[32:33]
	v_lshl_add_u64 v[2:3], v[2:3], 0, v[12:13]
	s_nop 0
	s_movk_i32 s0, 0xa00
	v_and_b32_e32 v57, 63, v54
	v_mul_lo_u32 v1, v1, s0
	v_readlane_b32 s1, v240, 18
	v_cndmask_b32_e64 v2, 0, 1, s[88:89]
	v_lshlrev_b32_e32 v3, 2, v57
	v_add_u32_e32 v55, 16, v1
	v_add_u32_e32 v9, s1, v1
	v_cmp_ne_u32_e64 s[40:41], 1, v2
	v_add_u32_e32 v1, v55, v3
	v_add_u32_e32 v2, v9, v3
	ds_write2st64_b32 v1, v8, v8 offset0:148 offset1:149
	ds_write2st64_b32 v1, v8, v8 offset0:150 offset1:151
	ds_write2st64_b32 v1, v8, v8 offset0:152 offset1:153
	ds_write2st64_b32 v1, v8, v8 offset0:154 offset1:155
	ds_write2st64_b32 v1, v8, v8 offset0:156 offset1:157
	ds_write2st64_b32 v2, v8, v8 offset1:1
	ds_write2st64_b32 v2, v8, v8 offset0:2 offset1:3
	ds_write2st64_b32 v2, v8, v8 offset0:4 offset1:5
	ds_write2st64_b32 v2, v8, v8 offset0:6 offset1:7
	ds_write2st64_b32 v2, v8, v8 offset0:8 offset1:9
	s_lshl_b32 s0, s74, 9
	s_waitcnt vmcnt(9)
	v_mov_b64_e32 v[156:157], v[216:217]
	v_mov_b64_e32 v[158:159], v[218:219]
	v_mov_b64_e32 v[160:161], v[220:221]
	v_mov_b64_e32 v[162:163], v[222:223]
	v_mov_b64_e32 v[168:169], v[224:225]
	v_mov_b64_e32 v[170:171], v[226:227]
	v_mov_b64_e32 v[172:173], v[228:229]
	v_mov_b64_e32 v[174:175], v[230:231]
	v_mov_b64_e32 v[4:5], v[188:189]
	v_mov_b64_e32 v[6:7], v[190:191]
	v_mov_b64_e32 v[26:27], v[192:193]
	v_mov_b64_e32 v[28:29], v[194:195]
	v_mov_b64_e32 v[22:23], v[196:197]
	v_mov_b64_e32 v[24:25], v[198:199]
	v_mov_b64_e32 v[18:19], v[200:201]
	v_mov_b64_e32 v[20:21], v[202:203]
	v_mov_b64_e32 v[14:15], v[204:205]
	v_mov_b64_e32 v[16:17], v[206:207]
	v_mov_b64_e32 v[10:11], v[208:209]
	v_mov_b64_e32 v[12:13], v[210:211]
	s_sub_i32 s98, s2, s46
	s_cmp_lt_i32 s98, 0
	s_cselect_b32 s98, s2, s98
	s_mul_hi_u32 s99, s98, 0xf0f0f0f1
	s_lshr_b32 s100, s99, 7
	s_mul_i32 s101, s100, 0x88
	s_sub_i32 s98, s98, s101
	s_lshr_b32 s99, s99, 9
	s_and_b32 s100, s100, 3
	s_lshl_b32 s101, s98, 5
	s_cmp_gt_u32 s98, 7
	s_cbranch_scc1 .Lpf_lat_b
	s_lshl_b32 s99, s99, 8
	s_add_i32 s101, s101, 0x8000
	s_branch .Lpf_join_b
